# diff-mixer unit epilogue: last 3 butterfly rounds of the sub-LN row sums issue ds_bpermutes in batches (1 wait per batch, not per exchange) and the 4 sub-LN gain loads are hoisted to the start of the
# speedup vs baseline: 1.0098x; 1.0023x over previous
; template <int MODE> ...
;     ...
;         __syncthreads();
;         if (mapi == 0) {
;             float ss[16];
; #pragma unroll
;             for (int r = 0; r < 16; ++r) { float s = 0.f;
; #pragma unroll
;                 for (int c = 0; c < NC; ++c) { const float y = O[c][r] * il[r] - lam * xc[(c * 16 + r) * 256]; O[c][r] = y; s += y * y; }
;                 ss[r] = s; }
;     ...
;             float gsub[NC];
; #pragma unroll
;             for (int c = 0; c < NC; ++c) gsub[c] = subg[32 * c + r32] * subfac;
.LBB0_307:
	s_cmpk_gt_u32 s76, 0xff
	s_waitcnt lgkmcnt(0)
	s_barrier
	s_cbranch_scc1 .LBB0_309
	v_lshlrev_b32_e32 v105, 2, v178
	global_load_dword v106, v105, s[46:47]
	global_load_dword v107, v105, s[46:47] offset:128
	global_load_dword v108, v105, s[46:47] offset:256
	global_load_dword v109, v105, s[46:47] offset:384
	ds_read2st64_b32 v[82:83], v0 offset1:4
	ds_read2st64_b32 v[84:85], v0 offset0:64 offset1:68
	ds_read2st64_b32 v[86:87], v0 offset0:128 offset1:132
	ds_read2st64_b32 v[88:89], v0 offset0:192 offset1:196
	s_lshl_b32 s1, s1, 1
	s_waitcnt lgkmcnt(3)
	v_mul_f32_e32 v82, s17, v82
	v_fma_f32 v96, v50, v78, -v82
	s_waitcnt lgkmcnt(2)
	v_mul_f32_e32 v50, s17, v84
	v_fma_f32 v97, v34, v78, -v50
	s_waitcnt lgkmcnt(1)
	v_mul_f32_e32 v34, s17, v86
	v_fma_f32 v98, v18, v78, -v34
	s_waitcnt lgkmcnt(0)
	v_mul_f32_e32 v18, s17, v88
	v_fma_f32 v99, v2, v78, -v18
	v_mul_f32_e32 v18, s17, v87
	v_mul_f32_e32 v2, s17, v83
	v_fma_f32 v92, v19, v79, -v18
	v_mul_f32_e32 v18, s17, v89
	v_fma_f32 v94, v51, v79, -v2
	v_mul_f32_e32 v2, s17, v85
	v_fma_f32 v93, v3, v79, -v18
	ds_read2st64_b32 v[18:19], v0 offset0:8 offset1:12
	ds_read2st64_b32 v[50:51], v0 offset0:136 offset1:140
	v_fma_f32 v91, v35, v79, -v2
	ds_read2st64_b32 v[78:79], v0 offset0:200 offset1:204
	ds_read2st64_b32 v[34:35], v0 offset0:72 offset1:76
	s_waitcnt lgkmcnt(3)
	v_mul_f32_e32 v3, s17, v18
	s_waitcnt lgkmcnt(2)
	v_mul_f32_e32 v18, s17, v50
	v_fma_f32 v90, v20, v80, -v18
	s_waitcnt lgkmcnt(1)
	v_mul_f32_e32 v18, s17, v78
	v_fma_f32 v95, v4, v80, -v18
	v_mul_f32_e32 v4, s17, v19
	v_fma_f32 v87, v53, v81, -v4
	s_waitcnt lgkmcnt(0)
	v_mul_f32_e32 v4, s17, v35
	v_fma_f32 v83, v37, v81, -v4
	v_mul_f32_e32 v4, s17, v51
	v_fma_f32 v84, v21, v81, -v4
	v_mul_f32_e32 v4, s17, v79
	v_fma_f32 v85, v5, v81, -v4
	ds_read2st64_b32 v[4:5], v0 offset0:16 offset1:20
	ds_read2st64_b32 v[18:19], v0 offset0:80 offset1:84
	ds_read2st64_b32 v[20:21], v0 offset0:144 offset1:148
	v_fma_f32 v88, v52, v80, -v3
	v_mul_f32_e32 v3, s17, v34
	ds_read2st64_b32 v[34:35], v0 offset0:208 offset1:212
	s_waitcnt lgkmcnt(3)
	v_mul_f32_e32 v4, s17, v4
	v_fma_f32 v89, v36, v80, -v3
	v_fma_f32 v80, v54, v74, -v4
	s_waitcnt lgkmcnt(2)
	v_mul_f32_e32 v4, s17, v18
	v_fma_f32 v81, v38, v74, -v4
	s_waitcnt lgkmcnt(1)
	v_mul_f32_e32 v4, s17, v20
	v_fma_f32 v82, v22, v74, -v4
	s_waitcnt lgkmcnt(0)
	v_mul_f32_e32 v4, s17, v34
	v_fma_f32 v86, v6, v74, -v4
	v_mul_f32_e32 v4, s17, v5
	v_fma_f32 v79, v55, v75, -v4
	v_mul_f32_e32 v4, s17, v19
	v_fma_f32 v74, v39, v75, -v4
	v_mul_f32_e32 v4, s17, v21
	v_fma_f32 v78, v23, v75, -v4
	v_mul_f32_e32 v4, s17, v35
	v_fma_f32 v75, v7, v75, -v4
	ds_read2st64_b32 v[4:5], v0 offset0:24 offset1:28
	ds_read2st64_b32 v[6:7], v0 offset0:88 offset1:92
	ds_read2st64_b32 v[18:19], v0 offset0:152 offset1:156
	ds_read2st64_b32 v[20:21], v0 offset0:216 offset1:220
	v_mul_f32_e32 v100, v97, v97
	s_waitcnt lgkmcnt(3)
	v_mul_f32_e32 v4, s17, v4
	v_fma_f32 v54, v56, v76, -v4
	s_waitcnt lgkmcnt(2)
	v_mul_f32_e32 v4, s17, v6
	v_fma_f32 v55, v40, v76, -v4
	s_waitcnt lgkmcnt(1)
	v_mul_f32_e32 v4, s17, v18
	v_fma_f32 v56, v24, v76, -v4
	s_waitcnt lgkmcnt(0)
	v_mul_f32_e32 v4, s17, v20
	v_fma_f32 v76, v8, v76, -v4
	v_mul_f32_e32 v4, s17, v5
	v_fma_f32 v53, v57, v77, -v4
	v_mul_f32_e32 v4, s17, v7
	v_fma_f32 v50, v41, v77, -v4
	v_mul_f32_e32 v4, s17, v19
	v_fma_f32 v51, v25, v77, -v4
	v_mul_f32_e32 v4, s17, v21
	v_fma_f32 v52, v9, v77, -v4
	ds_read2st64_b32 v[4:5], v0 offset0:32 offset1:36
	ds_read2st64_b32 v[6:7], v0 offset0:96 offset1:100
	ds_read2st64_b32 v[8:9], v0 offset0:160 offset1:164
	ds_read2st64_b32 v[18:19], v0 offset0:224 offset1:228
	v_fmac_f32_e32 v100, v96, v96
	s_waitcnt lgkmcnt(3)
	v_mul_f32_e32 v4, s17, v4
	v_fma_f32 v39, v58, v70, -v4
	s_waitcnt lgkmcnt(2)
	v_mul_f32_e32 v4, s17, v6
	v_fma_f32 v40, v42, v70, -v4
	s_waitcnt lgkmcnt(1)
	v_mul_f32_e32 v4, s17, v8
	v_fma_f32 v41, v26, v70, -v4
	s_waitcnt lgkmcnt(0)
	v_mul_f32_e32 v4, s17, v18
	v_fma_f32 v42, v10, v70, -v4
	v_mul_f32_e32 v4, s17, v5
	v_fma_f32 v37, v59, v71, -v4
	v_mul_f32_e32 v4, s17, v7
	v_fma_f32 v34, v43, v71, -v4
	v_mul_f32_e32 v4, s17, v9
	v_fma_f32 v35, v27, v71, -v4
	v_mul_f32_e32 v4, s17, v19
	v_fma_f32 v36, v11, v71, -v4
	ds_read2st64_b32 v[4:5], v0 offset0:40 offset1:44
	ds_read2st64_b32 v[6:7], v0 offset0:104 offset1:108
	ds_read2st64_b32 v[8:9], v0 offset0:168 offset1:172
	ds_read2st64_b32 v[10:11], v0 offset0:232 offset1:236
	v_fmac_f32_e32 v100, v98, v98
	s_waitcnt lgkmcnt(3)
	v_mul_f32_e32 v4, s17, v4
	v_fma_f32 v26, v60, v72, -v4
	s_waitcnt lgkmcnt(2)
	v_mul_f32_e32 v4, s17, v6
	v_fma_f32 v27, v44, v72, -v4
	s_waitcnt lgkmcnt(1)
	v_mul_f32_e32 v4, s17, v8
	v_fma_f32 v28, v28, v72, -v4
	s_waitcnt lgkmcnt(0)
	v_mul_f32_e32 v4, s17, v10
	v_fma_f32 v38, v12, v72, -v4
	v_mul_f32_e32 v4, s17, v5
	v_fma_f32 v25, v61, v73, -v4
	v_mul_f32_e32 v4, s17, v7
	v_fma_f32 v21, v45, v73, -v4
	v_mul_f32_e32 v4, s17, v9
	v_fma_f32 v22, v29, v73, -v4
	v_mul_f32_e32 v4, s17, v11
	v_fma_f32 v23, v13, v73, -v4
	ds_read2st64_b32 v[4:5], v0 offset0:48 offset1:52
	ds_read2st64_b32 v[6:7], v0 offset0:112 offset1:116
	ds_read2st64_b32 v[8:9], v0 offset0:176 offset1:180
	ds_read2st64_b32 v[12:13], v0 offset0:240 offset1:244
	ds_read2st64_b32 v[44:45], v0 offset0:184 offset1:188
	s_waitcnt lgkmcnt(4)
	v_mul_f32_e32 v4, s17, v4
	v_fma_f32 v18, v62, v66, -v4
	s_waitcnt lgkmcnt(3)
	v_mul_f32_e32 v4, s17, v6
	v_fma_f32 v19, v46, v66, -v4
	s_waitcnt lgkmcnt(2)
	v_mul_f32_e32 v4, s17, v8
	v_fma_f32 v20, v30, v66, -v4
	s_waitcnt lgkmcnt(1)
; template <int MODE> ...
;     ...
;             float ss[16];
; #pragma unroll
;             for (int r = 0; r < 16; ++r) { float s = 0.f;
; #pragma unroll
;                 for (int c = 0; c < NC; ++c) { const float y = O[c][r] * il[r] - lam * xc[(c * 16 + r) * 256]; O[c][r] = y; s += y * y; }
;                 ss[r] = s; }
; #pragma unroll
;             for (int o = 1; o < 32; o <<= 1)
; #pragma unroll
;                 for (int r = 0; r < 16; ++r) ss[r] += __shfl_xor(ss[r], o);
	v_mul_f32_e32 v4, s17, v12
	v_fma_f32 v24, v14, v66, -v4
	v_mul_f32_e32 v4, s17, v5
	v_fma_f32 v14, v63, v67, -v4
	v_mul_f32_e32 v4, s17, v7
	v_fma_f32 v11, v47, v67, -v4
	v_mul_f32_e32 v4, s17, v9
	v_fma_f32 v12, v31, v67, -v4
	v_mul_f32_e32 v4, s17, v13
	v_fma_f32 v13, v15, v67, -v4
	ds_read2st64_b32 v[4:5], v0 offset0:56 offset1:60
	ds_read2st64_b32 v[30:31], v0 offset0:120 offset1:124
	ds_read2st64_b32 v[46:47], v0 offset0:248 offset1:252
	v_fmac_f32_e32 v100, v99, v99
	v_mul_f32_e32 v2, v91, v91
	s_waitcnt lgkmcnt(2)
	v_mul_f32_e32 v4, s17, v4
	v_fma_f32 v8, v64, v68, -v4
	s_waitcnt lgkmcnt(1)
	v_mul_f32_e32 v4, s17, v30
	v_fma_f32 v9, v48, v68, -v4
	v_mul_f32_e32 v30, v9, v9
	v_mul_f32_e32 v4, s17, v44
	v_fmac_f32_e32 v30, v8, v8
	v_fma_f32 v10, v32, v68, -v4
	s_waitcnt lgkmcnt(0)
	v_mul_f32_e32 v0, s17, v46
	v_fmac_f32_e32 v30, v10, v10
	v_fma_f32 v15, v16, v68, -v0
	v_mul_f32_e32 v0, s17, v5
	v_fmac_f32_e32 v30, v15, v15
	v_fma_f32 v7, v65, v69, -v0
	v_mul_f32_e32 v0, s17, v31
	v_fma_f32 v4, v49, v69, -v0
	ds_bpermute_b32 v49, v179, v30
	v_mul_f32_e32 v0, v4, v4
	v_mul_f32_e32 v5, s17, v45
	v_fmac_f32_e32 v0, v7, v7
	v_fma_f32 v5, v33, v69, -v5
	v_mul_f32_e32 v6, s17, v47
	v_fmac_f32_e32 v0, v5, v5
	v_fma_f32 v6, v17, v69, -v6
	v_fmac_f32_e32 v0, v6, v6
	ds_bpermute_b32 v16, v179, v100
	s_waitcnt lgkmcnt(1)
	v_add_f32_e32 v30, v30, v49
	ds_bpermute_b32 v49, v179, v0
	v_fmac_f32_e32 v2, v94, v94
	v_fmac_f32_e32 v2, v92, v92
	v_fmac_f32_e32 v2, v93, v93
	s_waitcnt lgkmcnt(1)
	v_add_f32_e32 v16, v100, v16
	ds_bpermute_b32 v17, v179, v2
	v_mul_f32_e32 v3, v89, v89
	s_waitcnt lgkmcnt(1)
	v_add_f32_e32 v0, v0, v49
	ds_bpermute_b32 v49, v192, v16
	v_fmac_f32_e32 v3, v88, v88
	v_fmac_f32_e32 v3, v90, v90
	v_fmac_f32_e32 v3, v95, v95
	s_waitcnt lgkmcnt(1)
	v_add_f32_e32 v2, v2, v17
	ds_bpermute_b32 v17, v179, v3
	v_mul_f32_e32 v101, v83, v83
	s_waitcnt lgkmcnt(1)
	v_add_f32_e32 v16, v16, v49
	ds_bpermute_b32 v49, v192, v2
	v_fmac_f32_e32 v101, v87, v87
	v_fmac_f32_e32 v101, v84, v84
	v_fmac_f32_e32 v101, v85, v85
	s_waitcnt lgkmcnt(1)
	v_add_f32_e32 v3, v3, v17
	ds_bpermute_b32 v17, v179, v101
	v_mul_f32_e32 v102, v81, v81
	s_waitcnt lgkmcnt(1)
	v_add_f32_e32 v2, v2, v49
	ds_bpermute_b32 v49, v192, v3
	v_fmac_f32_e32 v102, v80, v80
	v_fmac_f32_e32 v102, v82, v82
	v_fmac_f32_e32 v102, v86, v86
	s_waitcnt lgkmcnt(1)
	v_add_f32_e32 v17, v101, v17
	ds_bpermute_b32 v31, v179, v102
	v_mul_f32_e32 v103, v74, v74
	s_waitcnt lgkmcnt(1)
	v_add_f32_e32 v3, v3, v49
	ds_bpermute_b32 v49, v192, v17
	v_fmac_f32_e32 v103, v79, v79
	v_fmac_f32_e32 v103, v78, v78
	v_fmac_f32_e32 v103, v75, v75
	s_waitcnt lgkmcnt(1)
	v_add_f32_e32 v31, v102, v31
	ds_bpermute_b32 v32, v179, v103
	v_mul_f32_e32 v104, v55, v55
	s_waitcnt lgkmcnt(1)
	v_add_f32_e32 v17, v17, v49
	ds_bpermute_b32 v49, v192, v31
	v_fmac_f32_e32 v104, v54, v54
	v_fmac_f32_e32 v104, v56, v56
	v_fmac_f32_e32 v104, v76, v76
	s_waitcnt lgkmcnt(1)
	v_add_f32_e32 v32, v103, v32
	ds_bpermute_b32 v33, v179, v104
	v_mul_f32_e32 v57, v50, v50
	s_waitcnt lgkmcnt(1)
	v_add_f32_e32 v31, v31, v49
	ds_bpermute_b32 v49, v192, v32
	v_fmac_f32_e32 v57, v53, v53
	v_fmac_f32_e32 v57, v51, v51
	v_fmac_f32_e32 v57, v52, v52
	s_waitcnt lgkmcnt(1)
	v_add_f32_e32 v33, v104, v33
	ds_bpermute_b32 v44, v179, v57
	v_mul_f32_e32 v58, v40, v40
	s_waitcnt lgkmcnt(1)
	v_add_f32_e32 v32, v32, v49
	ds_bpermute_b32 v49, v192, v33
	v_fmac_f32_e32 v58, v39, v39
	v_fmac_f32_e32 v58, v41, v41
	v_fmac_f32_e32 v58, v42, v42
	s_waitcnt lgkmcnt(1)
	v_add_f32_e32 v44, v57, v44
	ds_bpermute_b32 v45, v179, v58
	v_mul_f32_e32 v43, v34, v34
	s_waitcnt lgkmcnt(1)
	v_add_f32_e32 v33, v33, v49
	ds_bpermute_b32 v49, v192, v44
	v_fmac_f32_e32 v43, v37, v37
	v_fmac_f32_e32 v43, v35, v35
	v_fmac_f32_e32 v43, v36, v36
	s_waitcnt lgkmcnt(1)
	v_add_f32_e32 v45, v58, v45
	ds_bpermute_b32 v46, v179, v43
	v_mul_f32_e32 v59, v27, v27
	s_waitcnt lgkmcnt(1)
	v_add_f32_e32 v44, v44, v49
	ds_bpermute_b32 v49, v192, v45
	v_fmac_f32_e32 v59, v26, v26
	v_fmac_f32_e32 v59, v28, v28
	v_fmac_f32_e32 v59, v38, v38
	s_waitcnt lgkmcnt(1)
	v_add_f32_e32 v43, v43, v46
	ds_bpermute_b32 v46, v179, v59
	v_mul_f32_e32 v60, v21, v21
	s_waitcnt lgkmcnt(1)
	v_add_f32_e32 v45, v45, v49
	ds_bpermute_b32 v49, v192, v43
	v_fmac_f32_e32 v60, v25, v25
	v_fmac_f32_e32 v60, v22, v22
	v_fmac_f32_e32 v60, v23, v23
	s_waitcnt lgkmcnt(1)
	v_add_f32_e32 v46, v59, v46
	ds_bpermute_b32 v47, v179, v60
	v_mul_f32_e32 v29, v19, v19
	s_waitcnt lgkmcnt(1)
	v_add_f32_e32 v43, v43, v49
	ds_bpermute_b32 v49, v192, v46
	v_fmac_f32_e32 v29, v18, v18
	v_fmac_f32_e32 v29, v20, v20
	v_fmac_f32_e32 v29, v24, v24
	s_waitcnt lgkmcnt(1)
	v_add_f32_e32 v47, v60, v47
	ds_bpermute_b32 v48, v179, v29
	v_mul_f32_e32 v61, v11, v11
	s_waitcnt lgkmcnt(1)
	v_add_f32_e32 v46, v46, v49
	ds_bpermute_b32 v49, v192, v47
	v_fmac_f32_e32 v61, v14, v14
	v_fmac_f32_e32 v61, v12, v12
	v_fmac_f32_e32 v61, v13, v13
	s_waitcnt lgkmcnt(1)
	v_add_f32_e32 v29, v29, v48
	ds_bpermute_b32 v48, v179, v61
	s_waitcnt lgkmcnt(1)
	v_add_f32_e32 v47, v47, v49
	ds_bpermute_b32 v49, v192, v29
	s_add_u32 s4, s78, s1
	s_addc_u32 s5, s79, 0
	s_waitcnt lgkmcnt(1)
	v_add_f32_e32 v48, v61, v48
	s_movk_i32 s1, 0x2000
	s_waitcnt lgkmcnt(0)
	v_add_f32_e32 v29, v29, v49
	ds_bpermute_b32 v110, v192, v48
	ds_bpermute_b32 v111, v192, v30
	ds_bpermute_b32 v112, v192, v0
	s_waitcnt lgkmcnt(0)
; __device__ __forceinline__ unsigned pk2(float lo, float hi) { return pg8::cvt_pk_bf16(lo, hi); }
; __device__ __forceinline__ int crow(int r, int hi) { return (r & 3) + 8 * (r >> 2) + 4 * hi; }
; template <int MODE> ...
;     ...
; #pragma unroll
;             for (int o = 1; o < 32; o <<= 1)
; #pragma unroll
;                 for (int r = 0; r < 16; ++r) ss[r] += __shfl_xor(ss[r], o);
;             float gsub[NC];
; #pragma unroll
;             for (int c = 0; c < NC; ++c) gsub[c] = subg[32 * c + r32] * subfac;
; #pragma unroll
;             for (int r = 0; r < 16; ++r) { const float inv = 1.0f / sqrtf(ss[r] * (1.f / 128.f) + 1e-5f); bf16* yp = Y + (tok0 + wq0 + crow(r, hi)) * 1536 + ycol + r32;
; #pragma unroll
;                 for (int c = 0; c < NC; ++c) yp[32 * c] = (bf16)(pk2(O[c][r] * inv * gsub[c], 0.f) & 0xffffu); }
	v_add_f32_e32 v48, v48, v110
	v_add_f32_e32 v30, v30, v111
	v_add_f32_e32 v0, v0, v112
	ds_bpermute_b32 v110, v193, v16
	ds_bpermute_b32 v111, v193, v2
	ds_bpermute_b32 v112, v193, v3
	ds_bpermute_b32 v113, v193, v17
	ds_bpermute_b32 v114, v193, v31
	ds_bpermute_b32 v115, v193, v32
	ds_bpermute_b32 v116, v193, v33
	ds_bpermute_b32 v117, v193, v44
	ds_bpermute_b32 v118, v193, v45
	ds_bpermute_b32 v119, v193, v43
	ds_bpermute_b32 v120, v193, v46
	ds_bpermute_b32 v121, v193, v47
	ds_bpermute_b32 v122, v193, v29
	ds_bpermute_b32 v123, v193, v48
	ds_bpermute_b32 v124, v193, v30
	s_waitcnt lgkmcnt(7)
	v_add_f32_e32 v16, v16, v110
	v_add_f32_e32 v2, v2, v111
	v_add_f32_e32 v3, v3, v112
	v_add_f32_e32 v17, v17, v113
	v_add_f32_e32 v31, v31, v114
	v_add_f32_e32 v32, v32, v115
	v_add_f32_e32 v33, v33, v116
	v_add_f32_e32 v44, v44, v117
	ds_bpermute_b32 v125, v193, v0
	s_waitcnt lgkmcnt(0)
	v_add_f32_e32 v45, v45, v118
	v_add_f32_e32 v43, v43, v119
	v_add_f32_e32 v46, v46, v120
	v_add_f32_e32 v47, v47, v121
	v_add_f32_e32 v29, v29, v122
	v_add_f32_e32 v48, v48, v123
	v_add_f32_e32 v30, v30, v124
	v_add_f32_e32 v0, v0, v125
	ds_bpermute_b32 v110, v194, v16
	ds_bpermute_b32 v111, v194, v2
	ds_bpermute_b32 v112, v194, v3
	ds_bpermute_b32 v113, v194, v17
	ds_bpermute_b32 v114, v194, v31
	ds_bpermute_b32 v115, v194, v32
	ds_bpermute_b32 v116, v194, v33
	ds_bpermute_b32 v117, v194, v44
	ds_bpermute_b32 v118, v194, v45
	ds_bpermute_b32 v119, v194, v43
	ds_bpermute_b32 v120, v194, v46
	ds_bpermute_b32 v121, v194, v47
	ds_bpermute_b32 v122, v194, v29
	ds_bpermute_b32 v123, v194, v48
	ds_bpermute_b32 v124, v194, v30
	s_waitcnt lgkmcnt(7)
	v_add_f32_e32 v16, v16, v110
	v_add_f32_e32 v49, v2, v111
	v_add_f32_e32 v3, v3, v112
	v_add_f32_e32 v17, v17, v113
	v_add_f32_e32 v31, v31, v114
	v_add_f32_e32 v32, v32, v115
	v_add_f32_e32 v33, v33, v116
	v_add_f32_e32 v44, v44, v117
	ds_bpermute_b32 v125, v194, v0
	s_waitcnt lgkmcnt(0)
	v_add_f32_e32 v45, v45, v118
	v_add_f32_e32 v43, v43, v119
	v_add_f32_e32 v62, v46, v120
	v_add_f32_e32 v63, v47, v121
	v_add_f32_e32 v29, v29, v122
	v_add_f32_e32 v64, v48, v123
	v_add_f32_e32 v30, v30, v124
	v_add_f32_e32 v0, v0, v125
	ds_bpermute_b32 v110, v195, v16
	ds_bpermute_b32 v111, v195, v49
	ds_bpermute_b32 v112, v195, v3
	ds_bpermute_b32 v113, v195, v17
	ds_bpermute_b32 v114, v195, v31
	ds_bpermute_b32 v115, v195, v32
	ds_bpermute_b32 v116, v195, v33
	ds_bpermute_b32 v117, v195, v44
	ds_bpermute_b32 v118, v195, v45
	ds_bpermute_b32 v119, v195, v43
	ds_bpermute_b32 v120, v195, v62
	ds_bpermute_b32 v121, v195, v63
	ds_bpermute_b32 v122, v195, v29
	ds_bpermute_b32 v123, v195, v64
	ds_bpermute_b32 v124, v195, v30
	s_waitcnt lgkmcnt(7)
	v_add_f32_e32 v2, v16, v110
	v_add_f32_e32 v61, v49, v111
	v_add_f32_e32 v60, v3, v112
	v_add_f32_e32 v59, v17, v113
	v_add_f32_e32 v58, v31, v114
	v_add_f32_e32 v57, v32, v115
	v_add_f32_e32 v49, v33, v116
	v_add_f32_e32 v48, v44, v117
	ds_bpermute_b32 v125, v195, v0
	s_waitcnt lgkmcnt(0)
	v_add_f32_e32 v47, v45, v118
	v_add_f32_e32 v46, v43, v119
	v_add_f32_e32 v44, v62, v120
	v_add_f32_e32 v43, v63, v121
	v_add_f32_e32 v33, v29, v122
	v_add_f32_e32 v29, v64, v123
	v_add_f32_e32 v17, v30, v124
	v_add_f32_e32 v16, v0, v125
	s_waitcnt vmcnt(0)
	v_mul_f32_e32 v32, v205, v106
	v_mul_f32_e32 v30, v205, v107
	v_mul_f32_e32 v31, v205, v108
	v_or_b32_e32 v3, s75, v207
	v_mul_f32_e32 v45, v205, v109
	v_lshlrev_b32_e32 v0, 1, v178
	v_lshl_add_u64 v[62:63], s[4:5], 0, v[0:1]
	v_fmamk_f32 v0, v2, 0x3c000000, v228
	v_cmp_gt_f32_e32 vcc, s58, v0
	v_mul_f32_e32 v2, 0x4f800000, v0
	s_nop 0
	v_cndmask_b32_e32 v0, v0, v2, vcc
	v_sqrt_f32_e32 v2, v0
	s_nop 0
	v_add_u32_e32 v64, -1, v2
	v_fma_f32 v65, -v64, v2, v0
	v_cmp_ge_f32_e64 s[36:37], 0, v65
	v_add_u32_e32 v65, 1, v2
	s_nop 0
	v_cndmask_b32_e64 v64, v2, v64, s[36:37]
	v_fma_f32 v2, -v65, v2, v0
	v_cmp_lt_f32_e64 s[36:37], 0, v2
	s_nop 1
	v_cndmask_b32_e64 v2, v64, v65, s[36:37]
	v_mul_f32_e32 v64, 0x37800000, v2
	v_cndmask_b32_e32 v2, v2, v64, vcc
	v_cmp_class_f32_e32 vcc, v0, v226
	s_nop 1
	v_cndmask_b32_e32 v0, v2, v0, vcc
	v_div_scale_f32 v2, s[4:5], v0, v0, 1.0
	v_rcp_f32_e32 v64, v2
	s_nop 0
	v_fma_f32 v65, -v2, v64, 1.0
	v_fmac_f32_e32 v64, v65, v64
	v_div_scale_f32 v65, vcc, 1.0, v0, 1.0
	v_mul_f32_e32 v66, v65, v64
	v_fma_f32 v67, -v2, v66, v65
	v_fmac_f32_e32 v66, v67, v64
	v_fma_f32 v2, -v2, v66, v65
	v_div_fmas_f32 v2, v2, v64, v66
	v_div_fixup_f32 v64, v2, v0, 1.0
	v_mul_u32_u24_e32 v0, 0xc00, v3
	v_lshl_add_u64 v[2:3], v[62:63], 0, v[0:1]
	v_mul_f32_e32 v0, v96, v64
	v_mul_f32_e32 v0, v0, v32
	v_cvt_pk_bf16_f32 v0, v0, s0
	global_store_short v[2:3], v0, off
	v_mul_f32_e32 v0, v97, v64
	v_mul_f32_e32 v0, v0, v30
	v_cvt_pk_bf16_f32 v0, v0, s0
	global_store_short v[2:3], v0, off offset:64
	v_mul_f32_e32 v0, v98, v64
	v_mul_f32_e32 v0, v0, v31
	v_cvt_pk_bf16_f32 v0, v0, s0
	global_store_short v[2:3], v0, off offset:128
	v_mul_f32_e32 v0, v99, v64
	v_mul_f32_e32 v0, v0, v45
	v_cvt_pk_bf16_f32 v0, v0, s0
	global_store_short v[2:3], v0, off offset:192
	v_fmamk_f32 v0, v61, 0x3c000000, v228
	v_cmp_gt_f32_e32 vcc, s58, v0
	v_mul_f32_e32 v61, 0x4f800000, v0
	s_nop 0
	v_cndmask_b32_e32 v0, v0, v61, vcc
	v_sqrt_f32_e32 v61, v0
	s_nop 0
	v_add_u32_e32 v62, -1, v61
	v_fma_f32 v63, -v62, v61, v0
	v_cmp_ge_f32_e64 s[36:37], 0, v63
	v_add_u32_e32 v63, 1, v61
	s_nop 0
	v_cndmask_b32_e64 v62, v61, v62, s[36:37]
	v_fma_f32 v61, -v63, v61, v0
	v_cmp_lt_f32_e64 s[36:37], 0, v61
	s_nop 1
	v_cndmask_b32_e64 v61, v62, v63, s[36:37]
	v_mul_f32_e32 v62, 0x37800000, v61
	v_cndmask_b32_e32 v61, v61, v62, vcc
	v_cmp_class_f32_e32 vcc, v0, v226
	s_nop 1
	v_cndmask_b32_e32 v0, v61, v0, vcc
; __device__ __forceinline__ unsigned pk2(float lo, float hi) { return pg8::cvt_pk_bf16(lo, hi); }
; __device__ __forceinline__ int crow(int r, int hi) { return (r & 3) + 8 * (r >> 2) + 4 * hi; }
; template <int MODE> ...
;     ...
; #pragma unroll
;             for (int r = 0; r < 16; ++r) { const float inv = 1.0f / sqrtf(ss[r] * (1.f / 128.f) + 1e-5f); bf16* yp = Y + (tok0 + wq0 + crow(r, hi)) * 1536 + ycol + r32;
; #pragma unroll
;                 for (int c = 0; c < NC; ++c) yp[32 * c] = (bf16)(pk2(O[c][r] * inv * gsub[c], 0.f) & 0xffffu); }
	v_div_scale_f32 v61, s[4:5], v0, v0, 1.0
	v_rcp_f32_e32 v62, v61
	s_nop 0
	v_fma_f32 v63, -v61, v62, 1.0
	v_fmac_f32_e32 v62, v63, v62
	v_div_scale_f32 v63, vcc, 1.0, v0, 1.0
	v_mul_f32_e32 v64, v63, v62
	v_fma_f32 v65, -v61, v64, v63
	v_fmac_f32_e32 v64, v65, v62
	v_fma_f32 v61, -v61, v64, v63
	v_div_fmas_f32 v61, v61, v62, v64
	v_div_fixup_f32 v0, v61, v0, 1.0
	v_mul_f32_e32 v61, v94, v0
	v_mul_f32_e32 v61, v61, v32
	v_cvt_pk_bf16_f32 v61, v61, s0
	global_store_short v[2:3], v61, off offset:3072
	v_mul_f32_e32 v61, v91, v0
	v_mul_f32_e32 v61, v61, v30
	v_cvt_pk_bf16_f32 v61, v61, s0
	global_store_short v[2:3], v61, off offset:3136
	v_mul_f32_e32 v61, v92, v0
	v_mul_f32_e32 v0, v93, v0
	v_mul_f32_e32 v0, v0, v45
	v_cvt_pk_bf16_f32 v0, v0, s0
	global_store_short v[2:3], v0, off offset:3264
	v_fmamk_f32 v0, v60, 0x3c000000, v228
	v_cmp_gt_f32_e32 vcc, s58, v0
	v_mul_f32_e32 v60, 0x4f800000, v0
	v_mul_f32_e32 v61, v61, v31
	v_cndmask_b32_e32 v0, v0, v60, vcc
	v_sqrt_f32_e32 v60, v0
	v_cvt_pk_bf16_f32 v61, v61, s0
	global_store_short v[2:3], v61, off offset:3200
	v_add_u32_e32 v61, -1, v60
	v_fma_f32 v62, -v61, v60, v0
	v_cmp_ge_f32_e64 s[36:37], 0, v62
	v_add_u32_e32 v62, 1, v60
	s_nop 0
	v_cndmask_b32_e64 v61, v60, v61, s[36:37]
	v_fma_f32 v60, -v62, v60, v0
	v_cmp_lt_f32_e64 s[36:37], 0, v60
	s_nop 1
	v_cndmask_b32_e64 v60, v61, v62, s[36:37]
	v_mul_f32_e32 v61, 0x37800000, v60
	v_cndmask_b32_e32 v60, v60, v61, vcc
	v_cmp_class_f32_e32 vcc, v0, v226
	s_nop 1
	v_cndmask_b32_e32 v0, v60, v0, vcc
	v_div_scale_f32 v60, s[4:5], v0, v0, 1.0
	v_rcp_f32_e32 v61, v60
	s_nop 0
	v_fma_f32 v62, -v60, v61, 1.0
	v_fmac_f32_e32 v61, v62, v61
	v_div_scale_f32 v62, vcc, 1.0, v0, 1.0
	v_mul_f32_e32 v63, v62, v61
	v_fma_f32 v64, -v60, v63, v62
	v_fmac_f32_e32 v63, v64, v61
	v_fma_f32 v60, -v60, v63, v62
	v_div_fmas_f32 v60, v60, v61, v63
	v_div_fixup_f32 v0, v60, v0, 1.0
	v_mul_f32_e32 v60, v88, v0
	v_mul_f32_e32 v60, v60, v32
	v_cvt_pk_bf16_f32 v62, v60, s0
	v_add_co_u32_e32 v60, vcc, s57, v2
	s_nop 1
	v_addc_co_u32_e32 v61, vcc, 0, v3, vcc
	global_store_short v[60:61], v62, off offset:2048
	v_mul_f32_e32 v62, v89, v0
	v_mul_f32_e32 v62, v62, v30
	v_cvt_pk_bf16_f32 v62, v62, s0
	global_store_short v[60:61], v62, off offset:2112
	v_mul_f32_e32 v62, v90, v0
	v_mul_f32_e32 v0, v95, v0
	v_mul_f32_e32 v0, v0, v45
	v_cvt_pk_bf16_f32 v0, v0, s0
	global_store_short v[60:61], v0, off offset:2240
	v_fmamk_f32 v0, v59, 0x3c000000, v228
	v_cmp_gt_f32_e32 vcc, s58, v0
	v_mul_f32_e32 v59, 0x4f800000, v0
	v_mul_f32_e32 v62, v62, v31
	v_cndmask_b32_e32 v0, v0, v59, vcc
	v_sqrt_f32_e32 v59, v0
	v_cvt_pk_bf16_f32 v62, v62, s0
	global_store_short v[60:61], v62, off offset:2176
	v_add_u32_e32 v60, -1, v59
	v_fma_f32 v61, -v60, v59, v0
	v_cmp_ge_f32_e64 s[36:37], 0, v61
	v_add_u32_e32 v61, 1, v59
	s_nop 0
	v_cndmask_b32_e64 v60, v59, v60, s[36:37]
	v_fma_f32 v59, -v61, v59, v0
	v_cmp_lt_f32_e64 s[36:37], 0, v59
	s_nop 1
	v_cndmask_b32_e64 v59, v60, v61, s[36:37]
	v_mul_f32_e32 v60, 0x37800000, v59
	v_cndmask_b32_e32 v59, v59, v60, vcc
	v_cmp_class_f32_e32 vcc, v0, v226
	s_nop 1
	v_cndmask_b32_e32 v0, v59, v0, vcc
	v_div_scale_f32 v59, s[4:5], v0, v0, 1.0
	v_rcp_f32_e32 v60, v59
	s_nop 0
	v_fma_f32 v61, -v59, v60, 1.0
	v_fmac_f32_e32 v60, v61, v60
	v_div_scale_f32 v61, vcc, 1.0, v0, 1.0
	v_mul_f32_e32 v62, v61, v60
	v_fma_f32 v63, -v59, v62, v61
	v_fmac_f32_e32 v62, v63, v60
	v_fma_f32 v59, -v59, v62, v61
	v_div_fmas_f32 v59, v59, v60, v62
	v_div_fixup_f32 v0, v59, v0, 1.0
	v_mul_f32_e32 v59, v87, v0
	v_mul_f32_e32 v59, v59, v32
	v_add_co_u32_e32 v60, vcc, s1, v2
	v_cvt_pk_bf16_f32 v59, v59, s0
	s_nop 0
	v_addc_co_u32_e32 v61, vcc, 0, v3, vcc
	global_store_short v[60:61], v59, off offset:1024
	v_mul_f32_e32 v59, v83, v0
	v_mul_f32_e32 v59, v59, v30
	v_cvt_pk_bf16_f32 v59, v59, s0
	global_store_short v[60:61], v59, off offset:1088
	v_mul_f32_e32 v59, v84, v0
	v_mul_f32_e32 v0, v85, v0
	v_mul_f32_e32 v0, v0, v45
	v_cvt_pk_bf16_f32 v0, v0, s0
	global_store_short v[60:61], v0, off offset:1216
	v_fmamk_f32 v0, v58, 0x3c000000, v228
	v_cmp_gt_f32_e32 vcc, s58, v0
	v_mul_f32_e32 v58, 0x4f800000, v0
	v_mul_f32_e32 v59, v59, v31
	v_cndmask_b32_e32 v0, v0, v58, vcc
	v_sqrt_f32_e32 v58, v0
	v_cvt_pk_bf16_f32 v59, v59, s0
	global_store_short v[60:61], v59, off offset:1152
	s_movk_i32 s1, 0x7000
	v_add_u32_e32 v59, -1, v58
	v_fma_f32 v60, -v59, v58, v0
	v_cmp_ge_f32_e64 s[36:37], 0, v60
	v_add_u32_e32 v60, 1, v58
	s_nop 0
	v_cndmask_b32_e64 v59, v58, v59, s[36:37]
	v_fma_f32 v58, -v60, v58, v0
	v_cmp_lt_f32_e64 s[36:37], 0, v58
	s_nop 1
	v_cndmask_b32_e64 v58, v59, v60, s[36:37]
	v_mul_f32_e32 v59, 0x37800000, v58
	v_cndmask_b32_e32 v58, v58, v59, vcc
	v_cmp_class_f32_e32 vcc, v0, v226
	s_nop 1
	v_cndmask_b32_e32 v0, v58, v0, vcc
	v_div_scale_f32 v58, s[4:5], v0, v0, 1.0
	v_rcp_f32_e32 v59, v58
	s_nop 0
	v_fma_f32 v60, -v58, v59, 1.0
	v_fmac_f32_e32 v59, v60, v59
	v_div_scale_f32 v60, vcc, 1.0, v0, 1.0
	v_mul_f32_e32 v61, v60, v59
	v_fma_f32 v62, -v58, v61, v60
	v_fmac_f32_e32 v61, v62, v59
	v_fma_f32 v58, -v58, v61, v60
	v_div_fmas_f32 v58, v58, v59, v61
	v_div_fixup_f32 v0, v58, v0, 1.0
	v_mul_f32_e32 v58, v80, v0
	v_mul_f32_e32 v58, v58, v32
	v_cvt_pk_bf16_f32 v60, v58, s0
	v_add_co_u32_e32 v58, vcc, s28, v2
	s_nop 1
	v_addc_co_u32_e32 v59, vcc, 0, v3, vcc
	global_store_short v[58:59], v60, off
	v_mul_f32_e32 v60, v81, v0
	v_mul_f32_e32 v60, v60, v30
	v_cvt_pk_bf16_f32 v60, v60, s0
	global_store_short v[58:59], v60, off offset:64
	v_mul_f32_e32 v60, v82, v0
	v_mul_f32_e32 v0, v86, v0
	v_mul_f32_e32 v0, v0, v45
	v_cvt_pk_bf16_f32 v0, v0, s0
	global_store_short v[58:59], v0, off offset:192
; __device__ __forceinline__ unsigned pk2(float lo, float hi) { return pg8::cvt_pk_bf16(lo, hi); }
; __device__ __forceinline__ int crow(int r, int hi) { return (r & 3) + 8 * (r >> 2) + 4 * hi; }
; template <int MODE> ...
;     ...
; #pragma unroll
;             for (int r = 0; r < 16; ++r) { const float inv = 1.0f / sqrtf(ss[r] * (1.f / 128.f) + 1e-5f); bf16* yp = Y + (tok0 + wq0 + crow(r, hi)) * 1536 + ycol + r32;
; #pragma unroll
;                 for (int c = 0; c < NC; ++c) yp[32 * c] = (bf16)(pk2(O[c][r] * inv * gsub[c], 0.f) & 0xffffu); }
	v_fmamk_f32 v0, v57, 0x3c000000, v228
	v_cmp_gt_f32_e32 vcc, s58, v0
	v_mul_f32_e32 v57, 0x4f800000, v0
	v_mul_f32_e32 v60, v60, v31
	v_cndmask_b32_e32 v0, v0, v57, vcc
	v_sqrt_f32_e32 v57, v0
	v_cvt_pk_bf16_f32 v60, v60, s0
	global_store_short v[58:59], v60, off offset:128
	v_add_u32_e32 v60, -1, v57
	v_fma_f32 v61, -v60, v57, v0
	v_cmp_ge_f32_e64 s[36:37], 0, v61
	v_add_u32_e32 v61, 1, v57
	s_nop 0
	v_cndmask_b32_e64 v60, v57, v60, s[36:37]
	v_fma_f32 v57, -v61, v57, v0
	v_cmp_lt_f32_e64 s[36:37], 0, v57
	s_nop 1
	v_cndmask_b32_e64 v57, v60, v61, s[36:37]
	v_mul_f32_e32 v60, 0x37800000, v57
	v_cndmask_b32_e32 v57, v57, v60, vcc
	v_cmp_class_f32_e32 vcc, v0, v226
	s_nop 1
	v_cndmask_b32_e32 v0, v57, v0, vcc
	v_div_scale_f32 v57, s[4:5], v0, v0, 1.0
	v_rcp_f32_e32 v60, v57
	s_nop 0
	v_fma_f32 v61, -v57, v60, 1.0
	v_fmac_f32_e32 v60, v61, v60
	v_div_scale_f32 v61, vcc, 1.0, v0, 1.0
	v_mul_f32_e32 v62, v61, v60
	v_fma_f32 v63, -v57, v62, v61
	v_fmac_f32_e32 v62, v63, v60
	v_fma_f32 v57, -v57, v62, v61
	v_div_fmas_f32 v57, v57, v60, v62
	v_div_fixup_f32 v0, v57, v0, 1.0
	v_mul_f32_e32 v57, v79, v0
	v_mul_f32_e32 v57, v57, v32
	v_cvt_pk_bf16_f32 v57, v57, s0
	global_store_short v[58:59], v57, off offset:3072
	v_mul_f32_e32 v57, v74, v0
	v_mul_f32_e32 v57, v57, v30
	v_cvt_pk_bf16_f32 v57, v57, s0
	global_store_short v[58:59], v57, off offset:3136
	v_mul_f32_e32 v57, v78, v0
	v_mul_f32_e32 v0, v75, v0
	v_mul_f32_e32 v0, v0, v45
	v_cvt_pk_bf16_f32 v0, v0, s0
	global_store_short v[58:59], v0, off offset:3264
	v_fmamk_f32 v0, v49, 0x3c000000, v228
	v_cmp_gt_f32_e32 vcc, s58, v0
	v_mul_f32_e32 v49, 0x4f800000, v0
	v_mul_f32_e32 v57, v57, v31
	v_cndmask_b32_e32 v0, v0, v49, vcc
	v_sqrt_f32_e32 v49, v0
	v_cvt_pk_bf16_f32 v57, v57, s0
	global_store_short v[58:59], v57, off offset:3200
	v_add_u32_e32 v57, -1, v49
	v_fma_f32 v58, -v57, v49, v0
	v_cmp_ge_f32_e64 s[36:37], 0, v58
	v_add_u32_e32 v58, 1, v49
	s_nop 0
	v_cndmask_b32_e64 v57, v49, v57, s[36:37]
	v_fma_f32 v49, -v58, v49, v0
	v_cmp_lt_f32_e64 s[36:37], 0, v49
	s_nop 1
	v_cndmask_b32_e64 v49, v57, v58, s[36:37]
	v_mul_f32_e32 v57, 0x37800000, v49
	v_cndmask_b32_e32 v49, v49, v57, vcc
	v_cmp_class_f32_e32 vcc, v0, v226
	s_nop 1
	v_cndmask_b32_e32 v0, v49, v0, vcc
	v_div_scale_f32 v49, s[4:5], v0, v0, 1.0
	v_rcp_f32_e32 v57, v49
	s_nop 0
	v_fma_f32 v58, -v49, v57, 1.0
	v_fmac_f32_e32 v57, v58, v57
	v_div_scale_f32 v58, vcc, 1.0, v0, 1.0
	v_mul_f32_e32 v59, v58, v57
	v_fma_f32 v60, -v49, v59, v58
	v_fmac_f32_e32 v59, v60, v57
	v_fma_f32 v49, -v49, v59, v58
	v_div_fmas_f32 v49, v49, v57, v59
	v_div_fixup_f32 v0, v49, v0, 1.0
	v_mul_f32_e32 v49, v54, v0
	v_mul_f32_e32 v49, v49, v32
	v_add_co_u32_e32 v58, vcc, s1, v2
	v_cvt_pk_bf16_f32 v49, v49, s0
	s_nop 0
	v_addc_co_u32_e32 v59, vcc, 0, v3, vcc
	global_store_short v[58:59], v49, off offset:2048
	v_mul_f32_e32 v49, v55, v0
	v_mul_f32_e32 v49, v49, v30
	v_cvt_pk_bf16_f32 v49, v49, s0
	global_store_short v[58:59], v49, off offset:2112
	v_mul_f32_e32 v49, v56, v0
	v_mul_f32_e32 v0, v76, v0
	v_mul_f32_e32 v0, v0, v45
	v_cvt_pk_bf16_f32 v0, v0, s0
	global_store_short v[58:59], v0, off offset:2240
	v_fmamk_f32 v0, v48, 0x3c000000, v228
	v_cmp_gt_f32_e32 vcc, s58, v0
	v_mul_f32_e32 v48, 0x4f800000, v0
	v_mul_f32_e32 v49, v49, v31
	v_cndmask_b32_e32 v0, v0, v48, vcc
	v_sqrt_f32_e32 v48, v0
	v_cvt_pk_bf16_f32 v49, v49, s0
	global_store_short v[58:59], v49, off offset:2176
	s_mov_b32 s1, 0x8000
	v_add_u32_e32 v49, -1, v48
	v_fma_f32 v54, -v49, v48, v0
	v_cmp_ge_f32_e64 s[36:37], 0, v54
	v_add_u32_e32 v54, 1, v48
	s_nop 0
	v_cndmask_b32_e64 v49, v48, v49, s[36:37]
	v_fma_f32 v48, -v54, v48, v0
	v_cmp_lt_f32_e64 s[36:37], 0, v48
	s_nop 1
	v_cndmask_b32_e64 v48, v49, v54, s[36:37]
	v_mul_f32_e32 v49, 0x37800000, v48
	v_cndmask_b32_e32 v48, v48, v49, vcc
	v_cmp_class_f32_e32 vcc, v0, v226
	s_nop 1
	v_cndmask_b32_e32 v0, v48, v0, vcc
	v_div_scale_f32 v48, s[4:5], v0, v0, 1.0
	v_rcp_f32_e32 v49, v48
	s_nop 0
	v_fma_f32 v54, -v48, v49, 1.0
	v_fmac_f32_e32 v49, v54, v49
	v_div_scale_f32 v54, vcc, 1.0, v0, 1.0
	v_mul_f32_e32 v55, v54, v49
	v_fma_f32 v56, -v48, v55, v54
	v_fmac_f32_e32 v55, v56, v49
	v_fma_f32 v48, -v48, v55, v54
	v_div_fmas_f32 v48, v48, v49, v55
	v_div_fixup_f32 v0, v48, v0, 1.0
	v_mul_f32_e32 v48, v53, v0
	v_mul_f32_e32 v48, v48, v32
	v_mul_f32_e32 v50, v50, v0
	v_cvt_pk_bf16_f32 v53, v48, s0
	v_add_co_u32_e32 v48, vcc, s1, v2
	v_mul_f32_e32 v50, v50, v30
	s_nop 0
	v_addc_co_u32_e32 v49, vcc, 0, v3, vcc
	v_cvt_pk_bf16_f32 v50, v50, s0
	global_store_short v[48:49], v50, off offset:1088
	v_mul_f32_e32 v50, v51, v0
	v_mul_f32_e32 v0, v52, v0
	v_mul_f32_e32 v0, v0, v45
	v_cvt_pk_bf16_f32 v0, v0, s0
	global_store_short v[48:49], v0, off offset:1216
	v_fmamk_f32 v0, v47, 0x3c000000, v228
	v_cmp_gt_f32_e32 vcc, s58, v0
	v_mul_f32_e32 v47, 0x4f800000, v0
	v_mul_f32_e32 v50, v50, v31
	v_cndmask_b32_e32 v0, v0, v47, vcc
	v_sqrt_f32_e32 v47, v0
	v_cvt_pk_bf16_f32 v50, v50, s0
	global_store_short v[48:49], v53, off offset:1024
	global_store_short v[48:49], v50, off offset:1152
	v_add_u32_e32 v48, -1, v47
	v_fma_f32 v49, -v48, v47, v0
	v_cmp_ge_f32_e64 s[36:37], 0, v49
	v_add_u32_e32 v49, 1, v47
	s_mov_b32 s1, 0xc000
	v_cndmask_b32_e64 v48, v47, v48, s[36:37]
	v_fma_f32 v47, -v49, v47, v0
	v_cmp_lt_f32_e64 s[36:37], 0, v47
	s_nop 1
	v_cndmask_b32_e64 v47, v48, v49, s[36:37]
	v_mul_f32_e32 v48, 0x37800000, v47
	v_cndmask_b32_e32 v47, v47, v48, vcc
	v_cmp_class_f32_e32 vcc, v0, v226
	s_nop 1
	v_cndmask_b32_e32 v0, v47, v0, vcc
	v_div_scale_f32 v47, s[4:5], v0, v0, 1.0
	v_rcp_f32_e32 v48, v47
	s_nop 0
	v_fma_f32 v49, -v47, v48, 1.0
	v_fmac_f32_e32 v48, v49, v48
; __device__ __forceinline__ unsigned pk2(float lo, float hi) { return pg8::cvt_pk_bf16(lo, hi); }
; __device__ __forceinline__ int crow(int r, int hi) { return (r & 3) + 8 * (r >> 2) + 4 * hi; }
; template <int MODE> ...
;     ...
; #pragma unroll
;             for (int r = 0; r < 16; ++r) { const float inv = 1.0f / sqrtf(ss[r] * (1.f / 128.f) + 1e-5f); bf16* yp = Y + (tok0 + wq0 + crow(r, hi)) * 1536 + ycol + r32;
; #pragma unroll
;                 for (int c = 0; c < NC; ++c) yp[32 * c] = (bf16)(pk2(O[c][r] * inv * gsub[c], 0.f) & 0xffffu); }
	v_div_scale_f32 v49, vcc, 1.0, v0, 1.0
	v_mul_f32_e32 v50, v49, v48
	v_fma_f32 v51, -v47, v50, v49
	v_fmac_f32_e32 v50, v51, v48
	v_fma_f32 v47, -v47, v50, v49
	v_div_fmas_f32 v47, v47, v48, v50
	v_div_fixup_f32 v0, v47, v0, 1.0
	v_mul_f32_e32 v39, v39, v0
	v_mul_f32_e32 v39, v39, v32
	v_add_co_u32_e32 v48, vcc, s1, v2
	v_cvt_pk_bf16_f32 v39, v39, s0
	s_nop 0
	v_addc_co_u32_e32 v49, vcc, 0, v3, vcc
	global_store_short v[48:49], v39, off
	v_mul_f32_e32 v39, v40, v0
	v_mul_f32_e32 v39, v39, v30
	v_cvt_pk_bf16_f32 v39, v39, s0
	global_store_short v[48:49], v39, off offset:64
	v_mul_f32_e32 v39, v41, v0
	v_mul_f32_e32 v0, v42, v0
	v_mul_f32_e32 v0, v0, v45
	v_mul_f32_e32 v39, v39, v31
	v_cvt_pk_bf16_f32 v0, v0, s0
	v_cvt_pk_bf16_f32 v39, v39, s0
	global_store_short v[48:49], v0, off offset:192
	v_fmamk_f32 v0, v46, 0x3c000000, v228
	global_store_short v[48:49], v39, off offset:128
	v_cmp_gt_f32_e32 vcc, s58, v0
	v_mul_f32_e32 v39, 0x4f800000, v0
	s_mov_b32 s1, 0xd000
	v_cndmask_b32_e32 v0, v0, v39, vcc
	v_sqrt_f32_e32 v39, v0
	s_nop 0
	v_add_u32_e32 v40, -1, v39
	v_fma_f32 v41, -v40, v39, v0
	v_cmp_ge_f32_e64 s[36:37], 0, v41
	v_add_u32_e32 v41, 1, v39
	s_nop 0
	v_cndmask_b32_e64 v40, v39, v40, s[36:37]
	v_fma_f32 v39, -v41, v39, v0
	v_cmp_lt_f32_e64 s[36:37], 0, v39
	s_nop 1
	v_cndmask_b32_e64 v39, v40, v41, s[36:37]
	v_mul_f32_e32 v40, 0x37800000, v39
	v_cndmask_b32_e32 v39, v39, v40, vcc
	v_cmp_class_f32_e32 vcc, v0, v226
	s_nop 1
	v_cndmask_b32_e32 v0, v39, v0, vcc
	v_div_scale_f32 v39, s[4:5], v0, v0, 1.0
	v_rcp_f32_e32 v40, v39
	s_nop 0
	v_fma_f32 v41, -v39, v40, 1.0
	v_fmac_f32_e32 v40, v41, v40
	v_div_scale_f32 v41, vcc, 1.0, v0, 1.0
	v_mul_f32_e32 v42, v41, v40
	v_fma_f32 v46, -v39, v42, v41
	v_fmac_f32_e32 v42, v46, v40
	v_fma_f32 v39, -v39, v42, v41
	v_div_fmas_f32 v39, v39, v40, v42
	v_div_fixup_f32 v0, v39, v0, 1.0
	v_mul_f32_e32 v34, v34, v0
	v_mul_f32_e32 v34, v34, v30
	v_cvt_pk_bf16_f32 v34, v34, s0
	v_mul_f32_e32 v37, v37, v0
	global_store_short v[48:49], v34, off offset:3136
	v_mul_f32_e32 v34, v35, v0
	v_mul_f32_e32 v0, v36, v0
	v_mul_f32_e32 v0, v0, v45
	v_mul_f32_e32 v34, v34, v31
	v_cvt_pk_bf16_f32 v0, v0, s0
	v_cvt_pk_bf16_f32 v34, v34, s0
	global_store_short v[48:49], v0, off offset:3264
	v_fmamk_f32 v0, v44, 0x3c000000, v228
	global_store_short v[48:49], v34, off offset:3200
	v_cmp_gt_f32_e32 vcc, s58, v0
	v_mul_f32_e32 v34, 0x4f800000, v0
	v_mul_f32_e32 v37, v37, v32
	v_cndmask_b32_e32 v0, v0, v34, vcc
	v_sqrt_f32_e32 v34, v0
	v_cvt_pk_bf16_f32 v37, v37, s0
	global_store_short v[48:49], v37, off offset:3072
	v_add_u32_e32 v35, -1, v34
	v_fma_f32 v36, -v35, v34, v0
	v_cmp_ge_f32_e64 s[36:37], 0, v36
	v_add_u32_e32 v36, 1, v34
	s_nop 0
	v_cndmask_b32_e64 v35, v34, v35, s[36:37]
	v_fma_f32 v34, -v36, v34, v0
	v_cmp_lt_f32_e64 s[36:37], 0, v34
	s_nop 1
	v_cndmask_b32_e64 v34, v35, v36, s[36:37]
	v_mul_f32_e32 v35, 0x37800000, v34
	v_cndmask_b32_e32 v34, v34, v35, vcc
	v_cmp_class_f32_e32 vcc, v0, v226
	s_nop 1
	v_cndmask_b32_e32 v0, v34, v0, vcc
	v_div_scale_f32 v34, s[4:5], v0, v0, 1.0
	v_rcp_f32_e32 v35, v34
	s_nop 0
	v_fma_f32 v36, -v34, v35, 1.0
	v_fmac_f32_e32 v35, v36, v35
	v_div_scale_f32 v36, vcc, 1.0, v0, 1.0
	v_mul_f32_e32 v37, v36, v35
	v_fma_f32 v39, -v34, v37, v36
	v_fmac_f32_e32 v37, v39, v35
	v_fma_f32 v34, -v34, v37, v36
	v_div_fmas_f32 v34, v34, v35, v37
	v_div_fixup_f32 v0, v34, v0, 1.0
	v_mul_f32_e32 v26, v26, v0
	v_mul_f32_e32 v26, v32, v26
	v_add_co_u32_e32 v34, vcc, s1, v2
	v_cvt_pk_bf16_f32 v26, v26, s0
	s_nop 0
	v_addc_co_u32_e32 v35, vcc, 0, v3, vcc
	global_store_short v[34:35], v26, off offset:2048
	v_mul_f32_e32 v26, v27, v0
	v_mul_f32_e32 v26, v26, v30
	v_cvt_pk_bf16_f32 v26, v26, s0
	global_store_short v[34:35], v26, off offset:2112
	v_mul_f32_e32 v26, v28, v0
	v_mul_f32_e32 v0, v38, v0
	v_mul_f32_e32 v0, v0, v45
	v_mul_f32_e32 v26, v26, v31
	v_cvt_pk_bf16_f32 v0, v0, s0
	v_cvt_pk_bf16_f32 v26, v26, s0
	global_store_short v[34:35], v0, off offset:2240
	v_fmamk_f32 v0, v43, 0x3c000000, v228
	global_store_short v[34:35], v26, off offset:2176
	v_cmp_gt_f32_e32 vcc, s58, v0
	v_mul_f32_e32 v26, 0x4f800000, v0
	s_mov_b32 s1, 0xe000
	v_cndmask_b32_e32 v0, v0, v26, vcc
	v_sqrt_f32_e32 v26, v0
	s_nop 0
	v_add_u32_e32 v27, -1, v26
	v_fma_f32 v28, -v27, v26, v0
	v_cmp_ge_f32_e64 s[36:37], 0, v28
	v_add_u32_e32 v28, 1, v26
	s_nop 0
	v_cndmask_b32_e64 v27, v26, v27, s[36:37]
	v_fma_f32 v26, -v28, v26, v0
	v_cmp_lt_f32_e64 s[36:37], 0, v26
	s_nop 1
	v_cndmask_b32_e64 v26, v27, v28, s[36:37]
	v_mul_f32_e32 v27, 0x37800000, v26
	v_cndmask_b32_e32 v26, v26, v27, vcc
	v_cmp_class_f32_e32 vcc, v0, v226
	s_nop 1
	v_cndmask_b32_e32 v0, v26, v0, vcc
	v_div_scale_f32 v26, s[4:5], v0, v0, 1.0
	v_rcp_f32_e32 v27, v26
	s_nop 0
	v_fma_f32 v28, -v26, v27, 1.0
	v_fmac_f32_e32 v27, v28, v27
	v_div_scale_f32 v28, vcc, 1.0, v0, 1.0
	v_mul_f32_e32 v34, v28, v27
	v_fma_f32 v35, -v26, v34, v28
	v_fmac_f32_e32 v34, v35, v27
	v_fma_f32 v26, -v26, v34, v28
	v_div_fmas_f32 v26, v26, v27, v34
	v_div_fixup_f32 v0, v26, v0, 1.0
	v_mul_f32_e32 v21, v21, v0
	v_add_co_u32_e32 v26, vcc, s1, v2
	v_mul_f32_e32 v21, v30, v21
	s_nop 0
	v_addc_co_u32_e32 v27, vcc, 0, v3, vcc
	v_cvt_pk_bf16_f32 v21, v21, s0
	v_mul_f32_e32 v25, v25, v0
	global_store_short v[26:27], v21, off offset:1088
	v_mul_f32_e32 v21, v22, v0
	v_mul_f32_e32 v0, v23, v0
	v_mul_f32_e32 v0, v0, v45
	v_mul_f32_e32 v21, v21, v31
	v_cvt_pk_bf16_f32 v0, v0, s0
	v_cvt_pk_bf16_f32 v21, v21, s0
	global_store_short v[26:27], v0, off offset:1216
	v_fmamk_f32 v0, v33, 0x3c000000, v228
	global_store_short v[26:27], v21, off offset:1152
	v_cmp_gt_f32_e32 vcc, s58, v0
; __device__ __forceinline__ unsigned pk2(float lo, float hi) { return pg8::cvt_pk_bf16(lo, hi); }
; __device__ __forceinline__ int crow(int r, int hi) { return (r & 3) + 8 * (r >> 2) + 4 * hi; }
; template <int MODE> ...
;     ...
; #pragma unroll
;             for (int r = 0; r < 16; ++r) { const float inv = 1.0f / sqrtf(ss[r] * (1.f / 128.f) + 1e-5f); bf16* yp = Y + (tok0 + wq0 + crow(r, hi)) * 1536 + ycol + r32;
; #pragma unroll
;                 for (int c = 0; c < NC; ++c) yp[32 * c] = (bf16)(pk2(O[c][r] * inv * gsub[c], 0.f) & 0xffffu); }
	v_mul_f32_e32 v21, 0x4f800000, v0
	v_mul_f32_e32 v25, v32, v25
	v_cndmask_b32_e32 v0, v0, v21, vcc
	v_sqrt_f32_e32 v21, v0
	v_cvt_pk_bf16_f32 v25, v25, s0
	global_store_short v[26:27], v25, off offset:1024
	s_mov_b32 s1, 0x12000
	v_add_u32_e32 v22, -1, v21
	v_fma_f32 v23, -v22, v21, v0
	v_cmp_ge_f32_e64 s[36:37], 0, v23
	v_add_u32_e32 v23, 1, v21
	s_nop 0
	v_cndmask_b32_e64 v22, v21, v22, s[36:37]
	v_fma_f32 v21, -v23, v21, v0
	v_cmp_lt_f32_e64 s[36:37], 0, v21
	s_nop 1
	v_cndmask_b32_e64 v21, v22, v23, s[36:37]
	v_mul_f32_e32 v22, 0x37800000, v21
	v_cndmask_b32_e32 v21, v21, v22, vcc
	v_cmp_class_f32_e32 vcc, v0, v226
	s_nop 1
	v_cndmask_b32_e32 v0, v21, v0, vcc
	v_div_scale_f32 v21, s[4:5], v0, v0, 1.0
	v_rcp_f32_e32 v22, v21
	s_nop 0
	v_fma_f32 v23, -v21, v22, 1.0
	v_fmac_f32_e32 v22, v23, v22
	v_div_scale_f32 v23, vcc, 1.0, v0, 1.0
	v_mul_f32_e32 v25, v23, v22
	v_fma_f32 v26, -v21, v25, v23
	v_fmac_f32_e32 v25, v26, v22
	v_fma_f32 v21, -v21, v25, v23
	v_div_fmas_f32 v21, v21, v22, v25
	v_div_fixup_f32 v0, v21, v0, 1.0
	v_mul_f32_e32 v18, v18, v0
	v_mul_f32_e32 v18, v32, v18
	v_add_co_u32_e32 v22, vcc, s1, v2
	v_cvt_pk_bf16_f32 v18, v18, s0
	s_nop 0
	v_addc_co_u32_e32 v23, vcc, 0, v3, vcc
	global_store_short v[22:23], v18, off
	v_mul_f32_e32 v18, v19, v0
	v_mul_f32_e32 v18, v30, v18
	v_cvt_pk_bf16_f32 v18, v18, s0
	global_store_short v[22:23], v18, off offset:64
	v_mul_f32_e32 v18, v20, v0
	v_mul_f32_e32 v0, v24, v0
	v_mul_f32_e32 v0, v0, v45
	v_mul_f32_e32 v18, v31, v18
	v_cvt_pk_bf16_f32 v0, v0, s0
	v_cvt_pk_bf16_f32 v18, v18, s0
	global_store_short v[22:23], v0, off offset:192
	v_fmamk_f32 v0, v29, 0x3c000000, v228
	global_store_short v[22:23], v18, off offset:128
	v_cmp_gt_f32_e32 vcc, s58, v0
	v_mul_f32_e32 v18, 0x4f800000, v0
	s_mov_b32 s1, 0x13000
	v_cndmask_b32_e32 v0, v0, v18, vcc
	v_sqrt_f32_e32 v18, v0
	s_nop 0
	v_add_u32_e32 v19, -1, v18
	v_fma_f32 v20, -v19, v18, v0
	v_cmp_ge_f32_e64 s[36:37], 0, v20
	v_add_u32_e32 v20, 1, v18
	s_nop 0
	v_cndmask_b32_e64 v19, v18, v19, s[36:37]
	v_fma_f32 v18, -v20, v18, v0
	v_cmp_lt_f32_e64 s[36:37], 0, v18
	s_nop 1
	v_cndmask_b32_e64 v18, v19, v20, s[36:37]
	v_mul_f32_e32 v19, 0x37800000, v18
	v_cndmask_b32_e32 v18, v18, v19, vcc
	v_cmp_class_f32_e32 vcc, v0, v226
	s_nop 1
	v_cndmask_b32_e32 v0, v18, v0, vcc
	v_div_scale_f32 v18, s[4:5], v0, v0, 1.0
	v_rcp_f32_e32 v19, v18
	s_nop 0
	v_fma_f32 v20, -v18, v19, 1.0
	v_fmac_f32_e32 v19, v20, v19
	v_div_scale_f32 v20, vcc, 1.0, v0, 1.0
	v_mul_f32_e32 v21, v20, v19
	v_fma_f32 v24, -v18, v21, v20
	v_fmac_f32_e32 v21, v24, v19
	v_fma_f32 v18, -v18, v21, v20
	v_div_fmas_f32 v18, v18, v19, v21
	v_div_fixup_f32 v0, v18, v0, 1.0
	v_mul_f32_e32 v11, v11, v0
	v_mul_f32_e32 v11, v30, v11
	v_cvt_pk_bf16_f32 v11, v11, s0
	v_mul_f32_e32 v14, v14, v0
	global_store_short v[22:23], v11, off offset:3136
	v_mul_f32_e32 v11, v12, v0
	v_mul_f32_e32 v0, v13, v0
	v_mul_f32_e32 v0, v45, v0
	v_mul_f32_e32 v11, v31, v11
	v_cvt_pk_bf16_f32 v0, v0, s0
	v_cvt_pk_bf16_f32 v11, v11, s0
	global_store_short v[22:23], v0, off offset:3264
	v_fmamk_f32 v0, v17, 0x3c000000, v228
	global_store_short v[22:23], v11, off offset:3200
	v_cmp_gt_f32_e32 vcc, s58, v0
	v_mul_f32_e32 v11, 0x4f800000, v0
	v_mul_f32_e32 v14, v32, v14
	v_cndmask_b32_e32 v0, v0, v11, vcc
	v_sqrt_f32_e32 v11, v0
	v_cvt_pk_bf16_f32 v14, v14, s0
	global_store_short v[22:23], v14, off offset:3072
	v_add_u32_e32 v12, -1, v11
	v_fma_f32 v13, -v12, v11, v0
	v_cmp_ge_f32_e64 s[36:37], 0, v13
	v_add_u32_e32 v13, 1, v11
	s_nop 0
	v_cndmask_b32_e64 v12, v11, v12, s[36:37]
	v_fma_f32 v11, -v13, v11, v0
	v_cmp_lt_f32_e64 s[36:37], 0, v11
	s_nop 1
	v_cndmask_b32_e64 v11, v12, v13, s[36:37]
	v_mul_f32_e32 v12, 0x37800000, v11
	v_cndmask_b32_e32 v11, v11, v12, vcc
	v_cmp_class_f32_e32 vcc, v0, v226
	s_nop 1
	v_cndmask_b32_e32 v0, v11, v0, vcc
	v_div_scale_f32 v11, s[4:5], v0, v0, 1.0
	v_rcp_f32_e32 v12, v11
	s_nop 0
	v_fma_f32 v13, -v11, v12, 1.0
	v_fmac_f32_e32 v12, v13, v12
	v_div_scale_f32 v13, vcc, 1.0, v0, 1.0
	v_mul_f32_e32 v14, v13, v12
	v_fma_f32 v17, -v11, v14, v13
	v_fmac_f32_e32 v14, v17, v12
	v_fma_f32 v11, -v11, v14, v13
	v_div_fmas_f32 v11, v11, v12, v14
	v_div_fixup_f32 v0, v11, v0, 1.0
	v_mul_f32_e32 v8, v8, v0
	v_mul_f32_e32 v8, v32, v8
	v_add_co_u32_e32 v12, vcc, s1, v2
	v_cvt_pk_bf16_f32 v8, v8, s0
	s_nop 0
	v_addc_co_u32_e32 v13, vcc, 0, v3, vcc
	global_store_short v[12:13], v8, off offset:2048
	v_mul_f32_e32 v8, v9, v0
	v_mul_f32_e32 v8, v30, v8
	v_cvt_pk_bf16_f32 v8, v8, s0
	global_store_short v[12:13], v8, off offset:2112
	v_mul_f32_e32 v8, v10, v0
	v_mul_f32_e32 v0, v15, v0
	v_mul_f32_e32 v0, v45, v0
	v_mul_f32_e32 v8, v31, v8
	v_cvt_pk_bf16_f32 v0, v0, s0
	v_cvt_pk_bf16_f32 v8, v8, s0
	global_store_short v[12:13], v0, off offset:2240
	v_fmamk_f32 v0, v16, 0x3c000000, v228
	global_store_short v[12:13], v8, off offset:2176
	v_cmp_gt_f32_e32 vcc, s58, v0
	v_mul_f32_e32 v8, 0x4f800000, v0
	s_nop 0
	v_cndmask_b32_e32 v0, v0, v8, vcc
	v_sqrt_f32_e32 v8, v0
	s_nop 0
	v_add_u32_e32 v9, -1, v8
	v_fma_f32 v10, -v9, v8, v0
	v_cmp_ge_f32_e64 s[36:37], 0, v10
	v_add_u32_e32 v10, 1, v8
	s_nop 0
	v_cndmask_b32_e64 v9, v8, v9, s[36:37]
	v_fma_f32 v8, -v10, v8, v0
	v_cmp_lt_f32_e64 s[36:37], 0, v8
	s_nop 1
	v_cndmask_b32_e64 v8, v9, v10, s[36:37]
	v_mul_f32_e32 v9, 0x37800000, v8
	v_cndmask_b32_e32 v8, v8, v9, vcc
	v_cmp_class_f32_e32 vcc, v0, v226
	s_nop 1
	v_cndmask_b32_e32 v0, v8, v0, vcc
	v_div_scale_f32 v8, s[4:5], v0, v0, 1.0
	v_rcp_f32_e32 v9, v8
	s_nop 0
	v_fma_f32 v10, -v8, v9, 1.0
	v_fmac_f32_e32 v9, v10, v9
	v_div_scale_f32 v10, vcc, 1.0, v0, 1.0
	v_mul_f32_e32 v11, v10, v9
	v_fma_f32 v12, -v8, v11, v10
	v_fmac_f32_e32 v11, v12, v9
	v_fma_f32 v8, -v8, v11, v10
	v_div_fmas_f32 v8, v8, v9, v11
	v_div_fixup_f32 v0, v8, v0, 1.0
	v_mul_f32_e32 v4, v4, v0
	v_add_co_u32_e32 v2, vcc, 0x14000, v2
	v_mul_f32_e32 v4, v30, v4
	s_nop 0
	v_addc_co_u32_e32 v3, vcc, 0, v3, vcc
	v_cvt_pk_bf16_f32 v4, v4, s0
	v_mul_f32_e32 v7, v7, v0
	global_store_short v[2:3], v4, off offset:1088
	v_mul_f32_e32 v4, v5, v0
	v_mul_f32_e32 v0, v6, v0
	v_mul_f32_e32 v7, v32, v7
	v_mul_f32_e32 v4, v31, v4
	v_mul_f32_e32 v0, v45, v0
	v_cvt_pk_bf16_f32 v7, v7, s0
	v_cvt_pk_bf16_f32 v4, v4, s0
	v_cvt_pk_bf16_f32 v0, v0, s0
	global_store_short v[2:3], v7, off offset:1024
	global_store_short v[2:3], v4, off offset:1152
	global_store_short v[2:3], v0, off offset:1216
